# v23 + s_sleep removed from the five deferred grid-barrier wait loops (tight polling)
# baseline (speedup 1.0000x reference)
; __device__ __forceinline__ unsigned xb_ld(unsigned* p)              { return __hip_atomic_load(p, __ATOMIC_RELAXED, __HIP_MEMORY_SCOPE_AGENT); }
; #define XB_SPIN(cond, bar) do { unsigned _sp = 0; while (cond) { __builtin_amdgcn_s_sleep(1); \
;     if ((++_sp & 255u) == 0u) { if (xb_ld(&(bar)[XB_TMO])) break; if (_sp > XB_SPIN_CAP) { atomicAdd(&(bar)[XB_TMO], 1u); break; } } } } while (0)
; __device__ __forceinline__ void xcd_barrier(const int wv, const XcdBarrier& b) {
;     ...
;             XB_SPIN(xb_ld(&bar[XB_XGEN(b.x)]) == gen, bar);
.Lgwip_spin:
	global_load_dword v224, v[222:223], off sc1
	s_waitcnt vmcnt(0)
	v_cmp_ne_u32_e32 vcc, s100, v224
	s_cbranch_vccnz .Lgwip_got
	s_sub_u32 s101, s101, 1
	s_cmp_lg_u32 s101, 0
	s_cbranch_scc1 .Lgwip_spin
